# phase-offset tuning: the staggered (odd) teams enter each row-local chain 12 us late
# speedup vs baseline: 1.0006x; 1.0006x over previous
.LBB0_476:
	s_or_b64 exec, exec, s[0:1]
	s_mov_b64 s[0:1], 0
	s_waitcnt lgkmcnt(0)
	s_barrier
	s_mov_b32 s2, 0x8040
	s_bitcmp1_b32 s2, s80
	s_cbranch_scc0 .Lstg_skip
	s_bitcmp1_b32 s61, 6
	s_cbranch_scc0 .Lstg_skip
	s_memrealtime s[2:3]
	s_waitcnt lgkmcnt(0)
	s_add_u32 s6, s2, 1200
.Lstg_loop:
	s_sleep 4
	s_memrealtime s[2:3]
	s_waitcnt lgkmcnt(0)
	s_sub_u32 s7, s2, s6
	s_cmp_lt_i32 s7, 0
	s_cbranch_scc1 .Lstg_loop
.Lstg_skip:
.LBB0_477:
	s_and_b64 vcc, exec, s[0:1]
	s_cbranch_vccz .LBB0_9
	s_waitcnt vmcnt(0)
	s_barrier
	s_mov_b64 s[0:1], exec
	v_readlane_b32 s2, v255, 16
	v_readlane_b32 s3, v255, 17
	s_and_b64 s[2:3], s[0:1], s[2:3]
	s_mov_b64 exec, s[2:3]
	s_cbranch_execz .LBB0_8
	buffer_wbl2 sc1
	s_load_dwordx2 s[2:3], s[38:39], 0x58
	s_mov_b64 s[6:7], exec
	v_mbcnt_lo_u32_b32 v1, s6, 0
	v_mbcnt_hi_u32_b32 v1, s7, v1
	v_cmp_eq_u32_e32 vcc, 0, v1
	s_waitcnt lgkmcnt(0)
	global_load_dword v0, v129, s[2:3] offset:40
	s_and_saveexec_b64 s[12:13], vcc
	s_cbranch_execz .LBB0_481
	s_bcnt1_i32_b64 s6, s[6:7]
	v_mov_b32_e32 v2, s6
	global_atomic_add v2, v129, v2, s[2:3] offset:32 sc0
